# cumulative log-forget sum (workgroups 0..15) moved ahead of seam 2, out of phase C's critical path
# speedup vs baseline: 1.0015x; 1.0015x over previous
.LBB0_199:
	v_readlane_b32 s0, v255, 0
	s_nop 1
	s_cmp_gt_u32 s0, 15
	s_cbranch_scc1 .Lcumsum_skip
	v_readlane_b32 s0, v255, 0
	s_lshl_b32 s0, s0, 13
	s_mov_b32 s1, 0
	v_mov_b32_e32 v19, v204
	s_lshl_b64 s[0:1], s[0:1], 2
	s_add_u32 s2, s74, s0
	v_lshlrev_b32_e32 v4, 4, v19
	s_addc_u32 s3, s75, s1
	v_ashrrev_i32_e32 v5, 31, v4
	v_lshl_add_u64 v[10:11], v[4:5], 2, s[2:3]
	global_load_dwordx4 v[0:3], v[10:11], off
	global_load_dwordx4 v[6:9], v[10:11], off offset:16
	global_load_dwordx4 v[20:23], v[10:11], off offset:32
	global_load_dwordx4 v[24:27], v[10:11], off offset:48
	v_and_b32_e32 v28, 64, v188
	v_add_u32_e32 v10, -1, v188
	v_cmp_lt_i32_e32 vcc, v10, v28
	v_add_u32_e32 v18, -2, v188
	s_waitcnt vmcnt(3)
	v_add_f32_e32 v1, v0, v1
	v_add_f32_e32 v16, v2, v1
	v_add_f32_e32 v17, v3, v16
	s_waitcnt vmcnt(2)
	v_add_f32_e32 v14, v6, v17
	v_add_f32_e32 v15, v7, v14
	v_add_f32_e32 v12, v8, v15
	v_cndmask_b32_e32 v10, v10, v188, vcc
	v_add_f32_e32 v13, v9, v12
	v_lshlrev_b32_e32 v29, 2, v10
	s_waitcnt vmcnt(1)
	v_add_f32_e32 v10, v20, v13
	v_add_f32_e32 v11, v21, v10
	v_add_f32_e32 v8, v22, v11
	v_add_f32_e32 v9, v23, v8
	s_waitcnt vmcnt(0)
	v_add_f32_e32 v6, v24, v9
	v_add_f32_e32 v7, v25, v6
	v_add_f32_e32 v2, v26, v7
	v_add_f32_e32 v3, v27, v2
	ds_bpermute_b32 v20, v29, v3
	v_cmp_lt_i32_e32 vcc, v18, v28
	v_add_u32_e32 v22, -4, v188
	s_waitcnt lgkmcnt(0)
	v_add_f32_e32 v20, v3, v20
	v_cndmask_b32_e32 v21, v18, v188, vcc
	v_and_b32_e32 v18, 63, v19
	v_cmp_eq_u32_e32 vcc, 0, v18
	v_lshlrev_b32_e32 v21, 2, v21
	s_nop 0
	v_cndmask_b32_e32 v20, v20, v3, vcc
	ds_bpermute_b32 v21, v21, v20
	v_cmp_lt_i32_e32 vcc, v22, v28
	s_waitcnt lgkmcnt(0)
	v_add_f32_e32 v21, v20, v21
	v_cndmask_b32_e32 v22, v22, v188, vcc
	v_cmp_gt_u32_e32 vcc, 2, v18
	v_lshlrev_b32_e32 v22, 2, v22
	s_nop 0
	v_cndmask_b32_e32 v20, v21, v20, vcc
	ds_bpermute_b32 v21, v22, v20
	v_add_u32_e32 v22, -8, v188
	v_cmp_lt_i32_e32 vcc, v22, v28
	s_waitcnt lgkmcnt(0)
	v_add_f32_e32 v21, v20, v21
	v_cndmask_b32_e32 v22, v22, v188, vcc
	v_cmp_gt_u32_e32 vcc, 4, v18
	v_lshlrev_b32_e32 v22, 2, v22
	s_nop 0
	v_cndmask_b32_e32 v20, v21, v20, vcc
	ds_bpermute_b32 v21, v22, v20
	v_add_u32_e32 v22, -16, v188
	v_cmp_lt_i32_e32 vcc, v22, v28
	s_waitcnt lgkmcnt(0)
	v_add_f32_e32 v21, v20, v21
	v_cndmask_b32_e32 v22, v22, v188, vcc
	v_cmp_gt_u32_e32 vcc, 8, v18
	v_lshlrev_b32_e32 v22, 2, v22
	s_nop 0
	v_cndmask_b32_e32 v20, v21, v20, vcc
	ds_bpermute_b32 v21, v22, v20
	v_subrev_u32_e32 v22, 32, v188
	v_cmp_lt_i32_e32 vcc, v22, v28
	s_waitcnt lgkmcnt(0)
	v_add_f32_e32 v21, v20, v21
	v_cndmask_b32_e32 v22, v22, v188, vcc
	v_cmp_gt_u32_e32 vcc, 16, v18
	v_lshlrev_b32_e32 v22, 2, v22
	s_nop 0
	v_cndmask_b32_e32 v20, v21, v20, vcc
	ds_bpermute_b32 v22, v22, v20
	v_ashrrev_i32_e32 v21, 6, v19
	v_cmp_eq_u32_e32 vcc, 63, v18
	s_waitcnt lgkmcnt(0)
	v_add_f32_e32 v22, v20, v22
	s_and_saveexec_b64 s[2:3], vcc
	v_lshl_add_u32 v23, v21, 2, 16
	ds_write_b32 v23, v22
	s_or_b64 exec, exec, s[2:3]
	v_cmp_gt_u32_e32 vcc, 32, v18
	s_waitcnt lgkmcnt(0)
	s_barrier
	v_cndmask_b32_e32 v18, v22, v20, vcc
	v_sub_f32_e32 v18, v18, v3
	v_cmp_lt_i32_e32 vcc, 0, v21
	s_and_saveexec_b64 s[4:5], vcc
	s_cbranch_execz .LBB0_264
	v_cmp_lt_u32_e32 vcc, 7, v21
	v_mov_b32_e32 v20, 0
	s_and_saveexec_b64 s[6:7], vcc
	s_cbranch_execz .LBB0_259
	v_and_b32_e32 v20, 0x7ffffff8, v21
	s_mov_b32 s2, 0
	s_mov_b32 s3, 16
	s_mov_b64 s[8:9], 0

.LBB0_264:
	s_or_b64 exec, exec, s[4:5]
	s_add_u32 s0, s76, s0
	s_addc_u32 s1, s77, s1
	v_lshl_add_u64 v[4:5], v[4:5], 2, s[0:1]
	v_pk_add_f32 v[0:1], v[0:1], v[18:19] op_sel_hi:[1,0]
	s_mov_b32 s0, 0x3fb8aa3b
	v_pk_mul_f32 v[20:21], v[0:1], s[0:1] op_sel_hi:[1,0]
	v_pk_add_f32 v[0:1], v[14:15], v[18:19] op_sel_hi:[1,0]
	v_pk_add_f32 v[12:13], v[12:13], v[18:19] op_sel_hi:[1,0]
	v_pk_add_f32 v[8:9], v[8:9], v[18:19] op_sel_hi:[1,0]
	v_pk_mul_f32 v[14:15], v[12:13], s[0:1] op_sel_hi:[1,0]
	v_pk_mul_f32 v[12:13], v[0:1], s[0:1] op_sel_hi:[1,0]
	v_pk_add_f32 v[0:1], v[10:11], v[18:19] op_sel_hi:[1,0]
	v_pk_add_f32 v[16:17], v[16:17], v[18:19] op_sel_hi:[1,0]
	v_pk_mul_f32 v[10:11], v[8:9], s[0:1] op_sel_hi:[1,0]
	v_pk_mul_f32 v[8:9], v[0:1], s[0:1] op_sel_hi:[1,0]
	v_pk_add_f32 v[0:1], v[6:7], v[18:19] op_sel_hi:[1,0]
	v_pk_add_f32 v[2:3], v[2:3], v[18:19] op_sel_hi:[1,0]
	v_pk_mul_f32 v[22:23], v[16:17], s[0:1] op_sel_hi:[1,0]
	v_pk_mul_f32 v[2:3], v[2:3], s[0:1] op_sel_hi:[1,0]
	v_pk_mul_f32 v[0:1], v[0:1], s[0:1] op_sel_hi:[1,0]
	global_store_dwordx4 v[4:5], v[20:23], off
	global_store_dwordx4 v[4:5], v[12:15], off offset:16
	global_store_dwordx4 v[4:5], v[8:11], off offset:32
	global_store_dwordx4 v[4:5], v[0:3], off offset:48
	s_barrier
.Lcumsum_skip:
	s_getreg_b32 s2, hwreg(HW_REG_XCC_ID, 0, 4)
	s_waitcnt vmcnt(0)
	s_waitcnt lgkmcnt(0)
	s_barrier
	s_mov_b64 s[0:1], exec
	v_readlane_b32 s4, v255, 2
	v_readlane_b32 s5, v255, 3
	s_and_b64 s[4:5], s[0:1], s[4:5]
	s_mov_b64 exec, s[4:5]
	s_cbranch_execz .LBB0_251
	v_mov_b32_e32 v16, 0
	s_waitcnt vmcnt(0) expcnt(0) lgkmcnt(0)
	ds_read_b32 v2, v16
	ds_read_b32 v0, v16 offset:4
	s_and_b32 s28, s2, 15
	s_waitcnt lgkmcnt(1)
	v_cmp_ne_u32_e32 vcc, 0, v2
	s_cbranch_vccnz .LBB0_215
	s_add_u32 s4, s92, 0x1000
	s_addc_u32 s5, s93, 0
	s_add_u32 s6, s92, 0x1100
	s_addc_u32 s7, s93, 0
	s_add_u32 s8, s92, 0x1200
	v_readlane_b32 s2, v255, 1
	s_addc_u32 s9, s93, 0
	s_mul_i32 s2, s95, s2
	s_add_u32 s10, s92, 0x1300
	s_mul_i32 s2, s2, s94
	s_addc_u32 s11, s93, 0
	s_mov_b32 s3, 1
	s_branch .LBB0_203

.LBB0_250:
	s_or_b64 exec, exec, s[6:7]
	s_waitcnt vmcnt(0)
.LBB0_251:
	s_or_b64 exec, exec, s[0:1]
	s_waitcnt lgkmcnt(0)
	s_barrier
.LBB0_265:
	v_mov_b32_e32 v108, v204
	s_lshl_b32 s0, s44, 15
	v_ashrrev_i32_e32 v0, 2, v108
	v_bfi_b32 v109, -16, v0, v108
	v_lshlrev_b32_e32 v0, 7, v109
	s_add_u32 s0, s58, s0
	v_ashrrev_i32_e32 v1, 31, v0
	s_addc_u32 s1, s59, 0
	v_lshlrev_b64 v[0:1], 1, v[0:1]
	v_lshl_add_u64 v[2:3], s[0:1], 0, v[0:1]
	s_add_u32 s2, s0, 0x40000
	v_writelane_b32 v255, s0, 9
	s_addc_u32 s3, s1, 0
	v_bfe_u32 v110, v108, 4, 2
	v_writelane_b32 v255, s1, 10
	v_mov_b32_e32 v24, 0
	v_writelane_b32 v255, s2, 11
	v_lshlrev_b32_e32 v25, 3, v108
	v_lshlrev_b32_e32 v4, 4, v110
	v_mov_b32_e32 v5, v24
	v_writelane_b32 v255, s3, 12
	v_lshl_add_u64 v[0:1], s[2:3], 0, v[0:1]
	v_and_b32_e32 v111, 0x78, v25
	s_lshl_b32 s2, s44, 7
	v_lshl_add_u64 v[20:21], v[2:3], 0, v[4:5]
	v_lshl_add_u64 v[26:27], v[0:1], 0, v[4:5]
	v_or_b32_e32 v25, s2, v111
	global_load_dwordx4 v[0:3], v[20:21], off
	global_load_dwordx4 v[4:7], v[20:21], off offset:64
	global_load_dwordx4 v[8:11], v[26:27], off
	global_load_dwordx4 v[12:15], v[26:27], off offset:64
	global_load_dwordx4 v[16:19], v[20:21], off offset:128
	s_nop 0
	global_load_dwordx4 v[20:23], v[20:21], off offset:192
	s_nop 0
	global_load_dwordx4 v[28:31], v[26:27], off offset:128
	global_load_dwordx4 v[32:35], v[26:27], off offset:192
	v_lshlrev_b32_e32 v26, 2, v25
	v_mov_b32_e32 v27, v24
	v_lshl_add_u64 v[52:53], s[20:21], 0, v[26:27]
	s_mov_b64 s[0:1], 0x1000
	v_lshl_add_u64 v[44:45], v[52:53], 0, s[0:1]
	s_movk_i32 s0, 0x2000
	v_add_co_u32_e32 v40, vcc, s0, v52
	s_mov_b64 s[0:1], 0x2000
	v_lshl_add_u64 v[48:49], v[52:53], 0, s[0:1]
	s_mov_b64 s[0:1], 0x3000
	v_addc_co_u32_e32 v41, vcc, 0, v53, vcc
	v_lshl_add_u64 v[56:57], v[52:53], 0, s[0:1]
	s_movk_i32 s0, 0x3000
	v_add_co_u32_e32 v52, vcc, s0, v52
	global_load_dwordx4 v[36:39], v[40:41], off offset:-4096
	s_nop 0
	global_load_dwordx4 v[40:43], v[40:41], off
	s_nop 0
	global_load_dwordx4 v[44:47], v[44:45], off offset:16
	s_nop 0
	global_load_dwordx4 v[48:51], v[48:49], off offset:16
	v_addc_co_u32_e32 v53, vcc, 0, v53, vcc
	global_load_dwordx4 v[52:55], v[52:53], off
	s_nop 0
	global_load_dwordx4 v[56:59], v[56:57], off offset:16
	s_nop 0
	global_load_dwordx4 v[60:63], v26, s[20:21] offset:16
	global_load_dwordx4 v[64:67], v26, s[22:23] offset:16
	global_load_dwordx4 v[68:71], v26, s[20:21]
	global_load_dwordx4 v[72:75], v26, s[22:23]
	v_add_u32_e32 v26, s2, v109
	v_ashrrev_i32_e32 v27, 31, v26
	v_lshlrev_b64 v[26:27], 2, v[26:27]
	v_lshl_add_u64 v[76:77], s[26:27], 0, v[26:27]
	global_load_dword v113, v[76:77], off
	v_lshl_add_u64 v[76:77], s[38:39], 0, v[26:27]
	v_lshl_add_u64 v[26:27], s[40:41], 0, v[26:27]
	global_load_dword v112, v[76:77], off
	global_load_dword v114, v[26:27], off
	v_ashrrev_i32_e32 v132, 4, v108
	v_lshlrev_b32_e32 v26, 1, v25
	v_mov_b32_e32 v27, v24
	s_lshl_b32 s0, s87, 6
	v_add_u32_e32 v133, -3, v132
	v_lshl_add_u64 v[126:127], s[68:69], 0, v[26:27]
	v_mov_b32_e32 v26, v24
	v_writelane_b32 v255, s2, 8
	v_add_u32_e32 v104, s0, v133
	v_mov_b32_e32 v25, v24
	v_mov_b64_e32 v[78:79], v[26:27]
	v_writelane_b32 v255, s0, 13
	v_cmp_lt_i32_e32 vcc, -1, v104
	v_mov_b64_e32 v[76:77], v[24:25]
	s_and_saveexec_b64 s[0:1], vcc
	s_cbranch_execz .LBB0_267
	v_mov_b32_e32 v105, v24
	v_lshlrev_b64 v[76:77], 11, v[104:105]
	v_lshl_add_u64 v[76:77], v[126:127], 0, v[76:77]
	global_load_dwordx4 v[76:79], v[76:77], off nt
